# v29 + P0b x0 loop row 1: scale-vector loads of blocks 1..3 hoisted, gain vectors reused from row 0's registers
# baseline (speedup 1.0000x reference)
; __device__ __forceinline__ unsigned pk2(float lo, float hi) { return f2bf(lo) | (f2bf(hi) << 16); }
; __host__ __device__ __forceinline__ unsigned img_off(unsigned row, unsigned col, unsigned KT) { return (((row >> 8) * KT + (col >> 6)) << 14) + (((row >> 7) & 1u) << 13) + hl_off(row & 127u, col & 63u); }
; __device__ __forceinline__ float gain_clamp(float g) { return fabsf(g) < 1e-5f ? copysignf(1e-5f, g) : g; }
; __device__ __forceinline__ void phase_p0b(const Args& a) {
;     ...
;         for (int u = 0; u < 2; ++u) {
;             const int r = rr[u]; const bool lat = r < MLAT; const int bb = lat ? (r >> 12) : 4;
;             const int t = r & 4095; const float prow = (float)(t >> 6), pcol = (float)(t & 63);
;             float q = 0.f;
; #pragma unroll
;             for (int j = 0; j < 4; ++j) {
;                 const int k0 = 256 * j + 4 * lane;
;                 f32x4 vv = v[u][j];
;                 if (lat) {
; #pragma unroll
;                     for (int e = 0; e < 4; ++e) { const float ang = ((j < 2) ? prow : pcol) * omega[e]; vv[e] += (j & 1) ? __cosf(ang) : __sinf(ang); }
;                 }
;                 q += (vv[0] * vv[0] + vv[1] * vv[1]) + (vv[2] * vv[2] + vv[3] * vv[3]);
;                 const f32x4 gg = *(const f32x4*)(g1 + k0);
;                 const f32x4 sc = *(const f32x4*)(mod + (size_t)bb * NMODC + DM + k0);
;                 f32x4 gc = gg * (1.0f + sc);
; #pragma unroll
;                 for (int e = 0; e < 4; ++e) gc[e] = gain_clamp(gc[e]);
;                 const f32x4 y = vv * gc;
;                 if (okr[u]) {
;                     u32x2 w; w.x = pk2(y[0], y[1]); w.y = pk2(y[2], y[3]); *(u32x2*)(XG + img_off((unsigned)r, (unsigned)k0, 16u)) = w;
;                 }
.LBB0_113:
	s_or_b64 exec, exec, s[0:1]
	v_min_i32_e32 v18, 0x4000, v73
	v_ashrrev_i32_e32 v18, 12, v18
	v_readlane_b32 s8, v251, 0
	v_lshrrev_b32_e32 v22, 3, v73
	s_waitcnt lgkmcnt(0)
	v_lshlrev_b32_e32 v23, 5, v73
	v_lshlrev_b32_e32 v24, 1, v73
	v_mul_hi_i32_i24_e32 v19, 0x6000, v18
	v_mul_i32_i24_e32 v18, 0x6000, v18
	v_readlane_b32 s22, v251, 14
	v_readlane_b32 s23, v251, 15
	v_lshlrev_b32_e32 v20, 6, v73
	v_and_or_b32 v22, v22, 14, v62
	v_and_b32_e32 v23, 0x1e0, v23
	v_and_b32_e32 v24, 16, v24
	v_lshl_add_u64 v[18:19], s[22:23], 0, v[18:19]
	s_mov_b64 s[0:1], 0x1000
	v_and_b32_e32 v20, 0x2000, v20
	v_lshlrev_b32_e32 v22, 9, v22
	v_bitop3_b32 v23, v23, v24, v63 bitop3:0x36
	v_lshl_add_u64 v[18:19], v[18:19], 0, s[0:1]
	v_or3_b32 v20, v23, v22, v20
	v_readlane_b32 s9, v251, 1
	v_readlane_b32 s10, v251, 2
	v_readlane_b32 s11, v251, 3
	v_readlane_b32 s12, v251, 4
	v_readlane_b32 s13, v251, 5
	v_readlane_b32 s14, v251, 6
	v_readlane_b32 s15, v251, 7
	v_readlane_b32 s16, v251, 8
	v_readlane_b32 s17, v251, 9
	v_readlane_b32 s18, v251, 10
	v_readlane_b32 s19, v251, 11
	v_readlane_b32 s20, v251, 12
	v_readlane_b32 s21, v251, 13
	s_and_saveexec_b64 s[42:43], s[38:39]
	s_cbranch_execz .LBB0_115
	v_lshl_add_u64 v[22:23], v[18:19], 0, v[206:207]
	global_load_dwordx4 v[22:25], v[22:23], off
	s_nop 0
	global_load_dwordx4 v[26:29], v[40:41], off
	v_lshlrev_b32_e32 v86, 2, v42
	v_mov_b32_e32 v87, v207
	v_lshl_add_u64 v[88:89], v[18:19], 0, v[86:87]
	global_load_dwordx4 v[120:123], v[88:89], off
	v_lshlrev_b32_e32 v86, 2, v44
	v_mov_b32_e32 v87, v207
	v_lshl_add_u64 v[90:91], v[18:19], 0, v[86:87]
	global_load_dwordx4 v[124:127], v[90:91], off
	v_lshlrev_b32_e32 v86, 2, v46
	v_mov_b32_e32 v87, v207
	v_lshl_add_u64 v[92:93], v[18:19], 0, v[86:87]
	global_load_dwordx4 v[128:131], v[92:93], off
	s_mov_b32 s0, 0x3fff00
	v_and_or_b32 v30, v74, s0, v43
	v_lshlrev_b32_e32 v30, 10, v30
	s_mov_b32 s0, 0xfffcc000
	v_and_or_b32 v206, v30, s0, v20
	s_brev_b32 s0, -2
	s_waitcnt vmcnt(1)
	v_pk_add_f32 v[24:25], v[24:25], 1.0 op_sel_hi:[1,0]
	v_pk_add_f32 v[22:23], v[22:23], 1.0 op_sel_hi:[1,0]
	s_waitcnt vmcnt(0)
	v_pk_mul_f32 v[24:25], v[28:29], v[24:25]
	v_pk_mul_f32 v[22:23], v[26:27], v[22:23]
	v_bfi_b32 v28, s0, v235, v24
	v_bfi_b32 v26, s0, v235, v22
	v_bfi_b32 v27, s0, v235, v23
	v_bfi_b32 v29, s0, v235, v25
	v_cmp_lt_f32_e64 s[0:1], |v23|, s28
	s_nop 1
	v_cndmask_b32_e64 v23, v23, v27, s[0:1]
	v_cmp_lt_f32_e64 s[0:1], |v22|, s28
	s_nop 1
	v_cndmask_b32_e64 v22, v22, v26, s[0:1]
	v_cmp_lt_f32_e64 s[0:1], |v25|, s28
	v_pk_mul_f32 v[22:23], v[14:15], v[22:23]
	s_nop 0
	v_cndmask_b32_e64 v25, v25, v29, s[0:1]
	v_cmp_lt_f32_e64 s[0:1], |v24|, s28
	v_bfe_u32 v26, v22, 16, 1
	v_bfe_u32 v27, v23, 16, 1
	v_cndmask_b32_e64 v24, v24, v28, s[0:1]
	v_pk_mul_f32 v[24:25], v[16:17], v[24:25]
	v_add3_u32 v22, v22, v26, s27
	v_bfe_u32 v28, v24, 16, 1
	v_bfe_u32 v29, v25, 16, 1
	v_add3_u32 v24, v24, v28, s27
	v_add3_u32 v23, v23, v27, s27
	v_add3_u32 v25, v25, v29, s27
	v_lshrrev_b32_e32 v22, 16, v22
	v_lshrrev_b32_e32 v24, 16, v24
	v_and_or_b32 v22, v23, s6, v22
	v_and_or_b32 v23, v25, s6, v24
	v_lshl_add_u64 v[24:25], v[206:207], 1, s[92:93]
	global_store_dwordx2 v[24:25], v[22:23], off

; __device__ __forceinline__ unsigned pk2(float lo, float hi) { return f2bf(lo) | (f2bf(hi) << 16); }
; __host__ __device__ __forceinline__ unsigned img_off(unsigned row, unsigned col, unsigned KT) { return (((row >> 8) * KT + (col >> 6)) << 14) + (((row >> 7) & 1u) << 13) + hl_off(row & 127u, col & 63u); }
; __device__ __forceinline__ float gain_clamp(float g) { return fabsf(g) < 1e-5f ? copysignf(1e-5f, g) : g; }
; __device__ __forceinline__ void phase_p0b(const Args& a) {
;     ...
;                 const f32x4 gg = *(const f32x4*)(g1 + k0);
;                 const f32x4 sc = *(const f32x4*)(mod + (size_t)bb * NMODC + DM + k0);
;                 f32x4 gc = gg * (1.0f + sc);
; #pragma unroll
;                 for (int e = 0; e < 4; ++e) gc[e] = gain_clamp(gc[e]);
;                 const f32x4 y = vv * gc;
;                 if (okr[u]) {
;                     u32x2 w; w.x = pk2(y[0], y[1]); w.y = pk2(y[2], y[3]); *(u32x2*)(XG + img_off((unsigned)r, (unsigned)k0, 16u)) = w;
.LBB0_117:
	s_or_b64 exec, exec, s[0:1]
	v_lshrrev_b32_e32 v21, 4, v73
	v_and_b32_e32 v21, 0x3fff0, v21
	s_and_saveexec_b64 s[42:43], s[38:39]
	s_cbranch_execz .LBB0_119
	v_mov_b32_e32 v55, v207
	v_lshl_add_u64 v[22:23], v[18:19], 0, v[54:55]
	s_nop 0
	s_nop 0
	s_nop 0
	s_brev_b32 s0, -2
	v_or_b32_e32 v30, v21, v37
	v_lshl_or_b32 v206, v30, 14, v20
	s_nop 0
	v_pk_add_f32 v[24:25], v[122:123], 1.0 op_sel_hi:[1,0]
	v_pk_add_f32 v[22:23], v[120:121], 1.0 op_sel_hi:[1,0]
	s_nop 0
	v_pk_mul_f32 v[24:25], v[110:111], v[24:25]
	v_pk_mul_f32 v[22:23], v[108:109], v[22:23]
	v_bfi_b32 v28, s0, v235, v24
	v_bfi_b32 v26, s0, v235, v22
	v_bfi_b32 v27, s0, v235, v23
	v_bfi_b32 v29, s0, v235, v25
	v_cmp_lt_f32_e64 s[0:1], |v23|, s28
	s_nop 1
	v_cndmask_b32_e64 v23, v23, v27, s[0:1]
	v_cmp_lt_f32_e64 s[0:1], |v22|, s28
	s_nop 1
	v_cndmask_b32_e64 v22, v22, v26, s[0:1]
	v_cmp_lt_f32_e64 s[0:1], |v25|, s28
	v_pk_mul_f32 v[22:23], v[10:11], v[22:23]
	s_nop 0
	v_cndmask_b32_e64 v25, v25, v29, s[0:1]
	v_cmp_lt_f32_e64 s[0:1], |v24|, s28
	v_bfe_u32 v26, v22, 16, 1
	v_bfe_u32 v27, v23, 16, 1
	v_cndmask_b32_e64 v24, v24, v28, s[0:1]
	v_pk_mul_f32 v[24:25], v[12:13], v[24:25]
	v_add3_u32 v22, v22, v26, s27
	v_bfe_u32 v28, v24, 16, 1
	v_bfe_u32 v29, v25, 16, 1
	v_add3_u32 v24, v24, v28, s27
	v_add3_u32 v23, v23, v27, s27
	v_add3_u32 v25, v25, v29, s27
	v_lshrrev_b32_e32 v22, 16, v22
	v_lshrrev_b32_e32 v24, 16, v24
	v_and_or_b32 v22, v23, s6, v22
	v_and_or_b32 v23, v25, s6, v24
	v_lshl_add_u64 v[24:25], v[206:207], 1, s[92:93]
	global_store_dwordx2 v[24:25], v[22:23], off

; __device__ __forceinline__ unsigned pk2(float lo, float hi) { return f2bf(lo) | (f2bf(hi) << 16); }
; __host__ __device__ __forceinline__ unsigned img_off(unsigned row, unsigned col, unsigned KT) { return (((row >> 8) * KT + (col >> 6)) << 14) + (((row >> 7) & 1u) << 13) + hl_off(row & 127u, col & 63u); }
; __device__ __forceinline__ float gain_clamp(float g) { return fabsf(g) < 1e-5f ? copysignf(1e-5f, g) : g; }
; __device__ __forceinline__ void phase_p0b(const Args& a) {
;     ...
;                 const f32x4 gg = *(const f32x4*)(g1 + k0);
;                 const f32x4 sc = *(const f32x4*)(mod + (size_t)bb * NMODC + DM + k0);
;                 f32x4 gc = gg * (1.0f + sc);
; #pragma unroll
;                 for (int e = 0; e < 4; ++e) gc[e] = gain_clamp(gc[e]);
;                 const f32x4 y = vv * gc;
;                 if (okr[u]) {
;                     u32x2 w; w.x = pk2(y[0], y[1]); w.y = pk2(y[2], y[3]); *(u32x2*)(XG + img_off((unsigned)r, (unsigned)k0, 16u)) = w;
.LBB0_124:
	v_mov_b32_e32 v53, v207
	v_lshl_add_u64 v[24:25], v[18:19], 0, v[52:53]
	s_nop 0
	s_nop 0
	s_nop 0
	v_or_b32_e32 v23, v21, v70
	s_brev_b32 s0, -2
	v_lshl_or_b32 v206, v23, 14, v20
	s_nop 0
	v_pk_add_f32 v[26:27], v[126:127], 1.0 op_sel_hi:[1,0]
	v_pk_add_f32 v[24:25], v[124:125], 1.0 op_sel_hi:[1,0]
	s_nop 0
	v_pk_mul_f32 v[26:27], v[114:115], v[26:27]
	v_pk_mul_f32 v[24:25], v[112:113], v[24:25]
	v_bfi_b32 v29, s0, v235, v26
	v_bfi_b32 v23, s0, v235, v24
	v_bfi_b32 v28, s0, v235, v25
	v_bfi_b32 v30, s0, v235, v27
	v_cmp_lt_f32_e64 s[0:1], |v25|, s28
	s_nop 1
	v_cndmask_b32_e64 v25, v25, v28, s[0:1]
	v_cmp_lt_f32_e64 s[0:1], |v24|, s28
	s_nop 1
	v_cndmask_b32_e64 v24, v24, v23, s[0:1]
	v_cmp_lt_f32_e64 s[0:1], |v27|, s28
	v_pk_mul_f32 v[24:25], v[6:7], v[24:25]
	s_nop 0
	v_cndmask_b32_e64 v27, v27, v30, s[0:1]
	v_cmp_lt_f32_e64 s[0:1], |v26|, s28
	v_bfe_u32 v23, v24, 16, 1
	v_bfe_u32 v28, v25, 16, 1
	v_cndmask_b32_e64 v26, v26, v29, s[0:1]
	v_pk_mul_f32 v[26:27], v[8:9], v[26:27]
	v_add3_u32 v23, v24, v23, s27
	v_bfe_u32 v29, v26, 16, 1
	v_bfe_u32 v30, v27, 16, 1
	v_add3_u32 v24, v25, v28, s27
	v_add3_u32 v25, v26, v29, s27
	v_add3_u32 v26, v27, v30, s27
	v_lshrrev_b32_e32 v23, 16, v23
	v_lshrrev_b32_e32 v25, 16, v25
	v_and_or_b32 v24, v24, s6, v23
	v_and_or_b32 v25, v26, s6, v25
	v_lshl_add_u64 v[26:27], v[206:207], 1, s[92:93]
	global_store_dwordx2 v[26:27], v[24:25], off
	s_or_b64 exec, exec, s[42:43]
	s_and_saveexec_b64 s[0:1], s[40:41]
	s_cbranch_execnz .LBB0_122

; __device__ __forceinline__ unsigned pk2(float lo, float hi) { return f2bf(lo) | (f2bf(hi) << 16); }
; __host__ __device__ __forceinline__ unsigned img_off(unsigned row, unsigned col, unsigned KT) { return (((row >> 8) * KT + (col >> 6)) << 14) + (((row >> 7) & 1u) << 13) + hl_off(row & 127u, col & 63u); }
; __device__ __forceinline__ float gain_clamp(float g) { return fabsf(g) < 1e-5f ? copysignf(1e-5f, g) : g; }
; __device__ __forceinline__ void phase_p0b(const Args& a) {
;     ...
;                 const f32x4 gg = *(const f32x4*)(g1 + k0);
;                 const f32x4 sc = *(const f32x4*)(mod + (size_t)bb * NMODC + DM + k0);
;                 f32x4 gc = gg * (1.0f + sc);
; #pragma unroll
;                 for (int e = 0; e < 4; ++e) gc[e] = gain_clamp(gc[e]);
;                 const f32x4 y = vv * gc;
;                 if (okr[u]) {
;                     u32x2 w; w.x = pk2(y[0], y[1]); w.y = pk2(y[2], y[3]); *(u32x2*)(XG + img_off((unsigned)r, (unsigned)k0, 16u)) = w;
.LBB0_126:
	v_mov_b32_e32 v57, v207
	v_lshl_add_u64 v[18:19], v[18:19], 0, v[56:57]
	s_nop 0
	s_nop 0
	v_or_b32_e32 v18, v21, v71
	v_lshl_or_b32 v206, v18, 14, v20
	s_brev_b32 s0, -2
	s_nop 0
	v_pk_add_f32 v[18:19], v[130:131], 1.0 op_sel_hi:[1,0]
	v_pk_add_f32 v[20:21], v[128:129], 1.0 op_sel_hi:[1,0]
	s_nop 0
	v_pk_mul_f32 v[18:19], v[118:119], v[18:19]
	v_pk_mul_f32 v[20:21], v[116:117], v[20:21]
	v_bfi_b32 v24, s0, v235, v18
	v_bfi_b32 v22, s0, v235, v20
	v_bfi_b32 v23, s0, v235, v21
	v_bfi_b32 v25, s0, v235, v19
	v_cmp_lt_f32_e64 s[0:1], |v21|, s28
	s_nop 1
	v_cndmask_b32_e64 v21, v21, v23, s[0:1]
	v_cmp_lt_f32_e64 s[0:1], |v20|, s28
	s_nop 1
	v_cndmask_b32_e64 v20, v20, v22, s[0:1]
	v_cmp_lt_f32_e64 s[0:1], |v19|, s28
	v_pk_mul_f32 v[20:21], v[2:3], v[20:21]
	s_nop 0
	v_cndmask_b32_e64 v19, v19, v25, s[0:1]
	v_cmp_lt_f32_e64 s[0:1], |v18|, s28
	v_bfe_u32 v22, v20, 16, 1
	v_bfe_u32 v23, v21, 16, 1
	v_cndmask_b32_e64 v18, v18, v24, s[0:1]
	v_pk_mul_f32 v[18:19], v[4:5], v[18:19]
	v_add3_u32 v20, v20, v22, s27
	v_bfe_u32 v24, v18, 16, 1
	v_bfe_u32 v25, v19, 16, 1
	v_add3_u32 v18, v18, v24, s27
	v_add3_u32 v21, v21, v23, s27
	v_add3_u32 v19, v19, v25, s27
	v_lshrrev_b32_e32 v20, 16, v20
	v_lshrrev_b32_e32 v22, 16, v18
	v_and_or_b32 v18, v21, s6, v20
	v_and_or_b32 v19, v19, s6, v22
	v_lshl_add_u64 v[20:21], v[206:207], 1, s[92:93]
	global_store_dwordx2 v[20:21], v[18:19], off
